# gate/up GEMM SwiGLU epilogue rewritten straight-line: same f32 op sequence with the non-transcendental steps as packed v_pk_mul/v_pk_add, batched exp/rcp, base address once per tile, permlane16_swap -
# speedup vs baseline: 1.0266x; 1.0147x over previous
.LBB0_1180:
	s_add_i32 s49, s49, 2
	s_cmp_lg_u32 s49, 16
	s_waitcnt lgkmcnt(0)
	s_mov_b32 s98, 1
	s_cbranch_scc1 .LBB0_1147
	s_mov_b32 s98, 0
	v_mfma_f32_16x16x32_bf16 v[98:101], v[210:213], v[178:181], v[98:101]
	v_mfma_f32_16x16x32_bf16 v[90:93], v[214:217], v[178:181], v[90:93]
	v_mfma_f32_16x16x32_bf16 v[94:97], v[218:221], v[178:181], v[94:97]
	v_mfma_f32_16x16x32_bf16 v[86:89], v[222:225], v[178:181], v[86:89]
	v_mfma_f32_16x16x32_bf16 v[82:85], v[210:213], v[182:185], v[82:85]
	v_mfma_f32_16x16x32_bf16 v[74:77], v[214:217], v[182:185], v[74:77]
	v_mfma_f32_16x16x32_bf16 v[78:81], v[218:221], v[182:185], v[78:81]
	v_mfma_f32_16x16x32_bf16 v[70:73], v[222:225], v[182:185], v[70:73]
	v_mfma_f32_16x16x32_bf16 v[62:65], v[210:213], v[186:189], v[62:65]
	v_mfma_f32_16x16x32_bf16 v[54:57], v[214:217], v[186:189], v[54:57]
	v_mfma_f32_16x16x32_bf16 v[58:61], v[218:221], v[186:189], v[58:61]
	v_mfma_f32_16x16x32_bf16 v[50:53], v[222:225], v[186:189], v[50:53]
	v_mfma_f32_16x16x32_bf16 v[46:49], v[210:213], v[190:193], v[46:49]
	v_mfma_f32_16x16x32_bf16 v[38:41], v[214:217], v[190:193], v[38:41]
	v_mfma_f32_16x16x32_bf16 v[42:45], v[218:221], v[190:193], v[42:45]
	v_mfma_f32_16x16x32_bf16 v[34:37], v[222:225], v[190:193], v[34:37]
	s_nop 7
	s_nop 7
	v_mov_b32_e32 v191, v0
	v_ashrrev_i32_e32 v190, 1, v191
	v_and_b32_e32 v192, 0xc0, v191
	v_and_b32_e32 v190, 0xffffff80, v190
	v_lshl_add_u32 v190, s38, 8, v190
	v_lshl_or_b32 v192, s34, 8, v192
	v_and_or_b32 v190, v191, 15, v190
	v_ashrrev_i32_e32 v192, 1, v192
	v_lshrrev_b32_e32 v191, 2, v191
	v_and_or_b32 v192, v191, 12, v192
	v_ashrrev_i32_e32 v193, 31, v192
	v_lshlrev_b64 v[184:185], 1, v[192:193]
	v_mov_b64_e32 v[182:183], s[6:7]
	v_mov_b32_e32 v174, 0xbfb8aa3b
	v_mov_b32_e32 v175, 0xbfb8aa3b
	v_mov_b32_e32 v176, 1.0
	v_mov_b32_e32 v177, 1.0
	v_mad_i64_i32 v[178:179], s[2:3], v190, s45, v[182:183]
	v_lshl_add_u64 v[178:179], v[178:179], 0, v[184:185]
	v_bfe_u32 v180, v0, 4, 1
	v_mul_u32_u24_e32 v180, 24, v180
	v_mov_b32_e32 v181, 0
	v_lshl_add_u64 v[178:179], v[178:179], 0, v[180:181]
	v_lshlrev_b32_e64 v180, 4, s45
	v_pk_mul_f32 v[166:167], v[158:159], v[174:175]
	v_pk_mul_f32 v[168:169], v[160:161], v[174:175]
	v_pk_mul_f32 v[170:171], v[150:151], v[174:175]
	v_pk_mul_f32 v[172:173], v[152:153], v[174:175]
	v_exp_f32_e32 v166, v166
	v_exp_f32_e32 v167, v167
	v_exp_f32_e32 v168, v168
	v_exp_f32_e32 v169, v169
	v_exp_f32_e32 v170, v170
	v_exp_f32_e32 v171, v171
	v_exp_f32_e32 v172, v172
	v_exp_f32_e32 v173, v173
	s_nop 0
	v_pk_add_f32 v[166:167], v[176:177], v[166:167]
	v_pk_add_f32 v[168:169], v[176:177], v[168:169]
	v_pk_add_f32 v[170:171], v[176:177], v[170:171]
	v_pk_add_f32 v[172:173], v[176:177], v[172:173]
	v_rcp_f32_e32 v166, v166
	v_rcp_f32_e32 v167, v167
	v_rcp_f32_e32 v168, v168
	v_rcp_f32_e32 v169, v169
	v_rcp_f32_e32 v170, v170
	v_rcp_f32_e32 v171, v171
	v_rcp_f32_e32 v172, v172
	v_rcp_f32_e32 v173, v173
	s_nop 0
	v_pk_mul_f32 v[166:167], v[158:159], v[166:167]
	v_pk_mul_f32 v[168:169], v[160:161], v[168:169]
	v_pk_mul_f32 v[170:171], v[150:151], v[170:171]
	v_pk_mul_f32 v[172:173], v[152:153], v[172:173]
	v_pk_mul_f32 v[154:155], v[154:155], v[166:167]
	v_pk_mul_f32 v[156:157], v[156:157], v[168:169]
	v_pk_mul_f32 v[146:147], v[146:147], v[170:171]
	v_pk_mul_f32 v[148:149], v[148:149], v[172:173]
	s_nop 0
	v_cvt_pk_bf16_f32 v158, v154, v155
	v_cvt_pk_bf16_f32 v159, v156, v157
	v_cvt_pk_bf16_f32 v160, v146, v147
	v_cvt_pk_bf16_f32 v161, v148, v149
	s_nop 1
	v_permlane16_swap_b32_e32 v158, v160
	v_permlane16_swap_b32_e32 v159, v161
	global_store_dwordx4 v[178:179], v[158:161], off
	v_mov_b32_e32 v181, 0
	v_lshl_add_u64 v[178:179], v[178:179], 0, v[180:181]
	v_pk_mul_f32 v[166:167], v[142:143], v[174:175]
	v_pk_mul_f32 v[168:169], v[144:145], v[174:175]
	v_pk_mul_f32 v[170:171], v[134:135], v[174:175]
	v_pk_mul_f32 v[172:173], v[136:137], v[174:175]
	v_exp_f32_e32 v166, v166
	v_exp_f32_e32 v167, v167
	v_exp_f32_e32 v168, v168
	v_exp_f32_e32 v169, v169
	v_exp_f32_e32 v170, v170
	v_exp_f32_e32 v171, v171
	v_exp_f32_e32 v172, v172
	v_exp_f32_e32 v173, v173
	s_nop 0
	v_pk_add_f32 v[166:167], v[176:177], v[166:167]
	v_pk_add_f32 v[168:169], v[176:177], v[168:169]
	v_pk_add_f32 v[170:171], v[176:177], v[170:171]
	v_pk_add_f32 v[172:173], v[176:177], v[172:173]
	v_rcp_f32_e32 v166, v166
	v_rcp_f32_e32 v167, v167
	v_rcp_f32_e32 v168, v168
	v_rcp_f32_e32 v169, v169
	v_rcp_f32_e32 v170, v170
	v_rcp_f32_e32 v171, v171
	v_rcp_f32_e32 v172, v172
	v_rcp_f32_e32 v173, v173
	s_nop 0
	v_pk_mul_f32 v[166:167], v[142:143], v[166:167]
	v_pk_mul_f32 v[168:169], v[144:145], v[168:169]
	v_pk_mul_f32 v[170:171], v[134:135], v[170:171]
	v_pk_mul_f32 v[172:173], v[136:137], v[172:173]
	v_pk_mul_f32 v[138:139], v[138:139], v[166:167]
	v_pk_mul_f32 v[140:141], v[140:141], v[168:169]
	v_pk_mul_f32 v[130:131], v[130:131], v[170:171]
	v_pk_mul_f32 v[132:133], v[132:133], v[172:173]
	s_nop 0
	v_cvt_pk_bf16_f32 v142, v138, v139
	v_cvt_pk_bf16_f32 v143, v140, v141
	v_cvt_pk_bf16_f32 v144, v130, v131
	v_cvt_pk_bf16_f32 v145, v132, v133
	s_nop 1
	v_permlane16_swap_b32_e32 v142, v144
	v_permlane16_swap_b32_e32 v143, v145
	global_store_dwordx4 v[178:179], v[142:145], off
	v_mov_b32_e32 v181, 0
	v_lshl_add_u64 v[178:179], v[178:179], 0, v[180:181]
	v_pk_mul_f32 v[166:167], v[126:127], v[174:175]
	v_pk_mul_f32 v[168:169], v[128:129], v[174:175]
	v_pk_mul_f32 v[170:171], v[118:119], v[174:175]
	v_pk_mul_f32 v[172:173], v[120:121], v[174:175]
	v_exp_f32_e32 v166, v166
	v_exp_f32_e32 v167, v167
	v_exp_f32_e32 v168, v168
	v_exp_f32_e32 v169, v169
	v_exp_f32_e32 v170, v170
	v_exp_f32_e32 v171, v171
	v_exp_f32_e32 v172, v172
	v_exp_f32_e32 v173, v173
	s_nop 0
	v_pk_add_f32 v[166:167], v[176:177], v[166:167]
	v_pk_add_f32 v[168:169], v[176:177], v[168:169]
	v_pk_add_f32 v[170:171], v[176:177], v[170:171]
	v_pk_add_f32 v[172:173], v[176:177], v[172:173]
	v_rcp_f32_e32 v166, v166
	v_rcp_f32_e32 v167, v167
	v_rcp_f32_e32 v168, v168
	v_rcp_f32_e32 v169, v169
	v_rcp_f32_e32 v170, v170
	v_rcp_f32_e32 v171, v171
	v_rcp_f32_e32 v172, v172
	v_rcp_f32_e32 v173, v173
	s_nop 0
	v_pk_mul_f32 v[166:167], v[126:127], v[166:167]
	v_pk_mul_f32 v[168:169], v[128:129], v[168:169]
	v_pk_mul_f32 v[170:171], v[118:119], v[170:171]
	v_pk_mul_f32 v[172:173], v[120:121], v[172:173]
	v_pk_mul_f32 v[122:123], v[122:123], v[166:167]
	v_pk_mul_f32 v[124:125], v[124:125], v[168:169]
	v_pk_mul_f32 v[114:115], v[114:115], v[170:171]
	v_pk_mul_f32 v[116:117], v[116:117], v[172:173]
	s_nop 0
	v_cvt_pk_bf16_f32 v126, v122, v123
	v_cvt_pk_bf16_f32 v127, v124, v125
	v_cvt_pk_bf16_f32 v128, v114, v115
	v_cvt_pk_bf16_f32 v129, v116, v117
	s_nop 1
	v_permlane16_swap_b32_e32 v126, v128
	v_permlane16_swap_b32_e32 v127, v129
	global_store_dwordx4 v[178:179], v[126:129], off
	v_mov_b32_e32 v181, 0
	v_lshl_add_u64 v[178:179], v[178:179], 0, v[180:181]
	v_pk_mul_f32 v[166:167], v[110:111], v[174:175]
	v_pk_mul_f32 v[168:169], v[112:113], v[174:175]
	v_pk_mul_f32 v[170:171], v[102:103], v[174:175]
	v_pk_mul_f32 v[172:173], v[104:105], v[174:175]
	v_exp_f32_e32 v166, v166
	v_exp_f32_e32 v167, v167
	v_exp_f32_e32 v168, v168
	v_exp_f32_e32 v169, v169
	v_exp_f32_e32 v170, v170
	v_exp_f32_e32 v171, v171
	v_exp_f32_e32 v172, v172
	v_exp_f32_e32 v173, v173
	s_nop 0
	v_pk_add_f32 v[166:167], v[176:177], v[166:167]
	v_pk_add_f32 v[168:169], v[176:177], v[168:169]
	v_pk_add_f32 v[170:171], v[176:177], v[170:171]
	v_pk_add_f32 v[172:173], v[176:177], v[172:173]
	v_rcp_f32_e32 v166, v166
	v_rcp_f32_e32 v167, v167
	v_rcp_f32_e32 v168, v168
	v_rcp_f32_e32 v169, v169
	v_rcp_f32_e32 v170, v170
	v_rcp_f32_e32 v171, v171
	v_rcp_f32_e32 v172, v172
	v_rcp_f32_e32 v173, v173
	s_nop 0
	v_pk_mul_f32 v[166:167], v[110:111], v[166:167]
	v_pk_mul_f32 v[168:169], v[112:113], v[168:169]
	v_pk_mul_f32 v[170:171], v[102:103], v[170:171]
	v_pk_mul_f32 v[172:173], v[104:105], v[172:173]
	v_pk_mul_f32 v[106:107], v[106:107], v[166:167]
	v_pk_mul_f32 v[108:109], v[108:109], v[168:169]
	v_pk_mul_f32 v[66:67], v[66:67], v[170:171]
	v_pk_mul_f32 v[68:69], v[68:69], v[172:173]
	s_nop 0
	v_cvt_pk_bf16_f32 v110, v106, v107
	v_cvt_pk_bf16_f32 v111, v108, v109
	v_cvt_pk_bf16_f32 v112, v66, v67
	v_cvt_pk_bf16_f32 v113, v68, v69
	s_nop 1
	v_permlane16_swap_b32_e32 v110, v112
	v_permlane16_swap_b32_e32 v111, v113
	global_store_dwordx4 v[178:179], v[110:113], off
	v_mov_b32_e32 v181, 0
	v_lshl_add_u64 v[178:179], v[178:179], 0, v[180:181]
	v_pk_mul_f32 v[166:167], v[98:99], v[174:175]
	v_pk_mul_f32 v[168:169], v[100:101], v[174:175]
	v_pk_mul_f32 v[170:171], v[90:91], v[174:175]
	v_pk_mul_f32 v[172:173], v[92:93], v[174:175]
	v_exp_f32_e32 v166, v166
	v_exp_f32_e32 v167, v167
	v_exp_f32_e32 v168, v168
	v_exp_f32_e32 v169, v169
	v_exp_f32_e32 v170, v170
	v_exp_f32_e32 v171, v171
	v_exp_f32_e32 v172, v172
	v_exp_f32_e32 v173, v173
	s_nop 0
	v_pk_add_f32 v[166:167], v[176:177], v[166:167]
	v_pk_add_f32 v[168:169], v[176:177], v[168:169]
	v_pk_add_f32 v[170:171], v[176:177], v[170:171]
	v_pk_add_f32 v[172:173], v[176:177], v[172:173]
	v_rcp_f32_e32 v166, v166
	v_rcp_f32_e32 v167, v167
	v_rcp_f32_e32 v168, v168
	v_rcp_f32_e32 v169, v169
	v_rcp_f32_e32 v170, v170
	v_rcp_f32_e32 v171, v171
	v_rcp_f32_e32 v172, v172
	v_rcp_f32_e32 v173, v173
	s_nop 0
	v_pk_mul_f32 v[166:167], v[98:99], v[166:167]
	v_pk_mul_f32 v[168:169], v[100:101], v[168:169]
	v_pk_mul_f32 v[170:171], v[90:91], v[170:171]
	v_pk_mul_f32 v[172:173], v[92:93], v[172:173]
	v_pk_mul_f32 v[94:95], v[94:95], v[166:167]
	v_pk_mul_f32 v[96:97], v[96:97], v[168:169]
	v_pk_mul_f32 v[86:87], v[86:87], v[170:171]
	v_pk_mul_f32 v[88:89], v[88:89], v[172:173]
	s_nop 0
	v_cvt_pk_bf16_f32 v98, v94, v95
	v_cvt_pk_bf16_f32 v99, v96, v97
	v_cvt_pk_bf16_f32 v100, v86, v87
	v_cvt_pk_bf16_f32 v101, v88, v89
	s_nop 1
	v_permlane16_swap_b32_e32 v98, v100
	v_permlane16_swap_b32_e32 v99, v101
	global_store_dwordx4 v[178:179], v[98:101], off
	v_mov_b32_e32 v181, 0
	v_lshl_add_u64 v[178:179], v[178:179], 0, v[180:181]
	v_pk_mul_f32 v[166:167], v[82:83], v[174:175]
	v_pk_mul_f32 v[168:169], v[84:85], v[174:175]
	v_pk_mul_f32 v[170:171], v[74:75], v[174:175]
	v_pk_mul_f32 v[172:173], v[76:77], v[174:175]
	v_exp_f32_e32 v166, v166
	v_exp_f32_e32 v167, v167
	v_exp_f32_e32 v168, v168
	v_exp_f32_e32 v169, v169
	v_exp_f32_e32 v170, v170
	v_exp_f32_e32 v171, v171
	v_exp_f32_e32 v172, v172
	v_exp_f32_e32 v173, v173
	s_nop 0
	v_pk_add_f32 v[166:167], v[176:177], v[166:167]
	v_pk_add_f32 v[168:169], v[176:177], v[168:169]
	v_pk_add_f32 v[170:171], v[176:177], v[170:171]
	v_pk_add_f32 v[172:173], v[176:177], v[172:173]
	v_rcp_f32_e32 v166, v166
	v_rcp_f32_e32 v167, v167
	v_rcp_f32_e32 v168, v168
	v_rcp_f32_e32 v169, v169
	v_rcp_f32_e32 v170, v170
	v_rcp_f32_e32 v171, v171
	v_rcp_f32_e32 v172, v172
	v_rcp_f32_e32 v173, v173
	s_nop 0
	v_pk_mul_f32 v[166:167], v[82:83], v[166:167]
	v_pk_mul_f32 v[168:169], v[84:85], v[168:169]
	v_pk_mul_f32 v[170:171], v[74:75], v[170:171]
	v_pk_mul_f32 v[172:173], v[76:77], v[172:173]
	v_pk_mul_f32 v[78:79], v[78:79], v[166:167]
	v_pk_mul_f32 v[80:81], v[80:81], v[168:169]
	v_pk_mul_f32 v[70:71], v[70:71], v[170:171]
	v_pk_mul_f32 v[72:73], v[72:73], v[172:173]
	s_nop 0
	v_cvt_pk_bf16_f32 v82, v78, v79
	v_cvt_pk_bf16_f32 v83, v80, v81
	v_cvt_pk_bf16_f32 v84, v70, v71
	v_cvt_pk_bf16_f32 v85, v72, v73
	s_nop 1
	v_permlane16_swap_b32_e32 v82, v84
	v_permlane16_swap_b32_e32 v83, v85
	global_store_dwordx4 v[178:179], v[82:85], off
	v_mov_b32_e32 v181, 0
	v_lshl_add_u64 v[178:179], v[178:179], 0, v[180:181]
	v_pk_mul_f32 v[166:167], v[62:63], v[174:175]
	v_pk_mul_f32 v[168:169], v[64:65], v[174:175]
	v_pk_mul_f32 v[170:171], v[54:55], v[174:175]
	v_pk_mul_f32 v[172:173], v[56:57], v[174:175]
	v_exp_f32_e32 v166, v166
	v_exp_f32_e32 v167, v167
	v_exp_f32_e32 v168, v168
	v_exp_f32_e32 v169, v169
	v_exp_f32_e32 v170, v170
	v_exp_f32_e32 v171, v171
	v_exp_f32_e32 v172, v172
	v_exp_f32_e32 v173, v173
	s_nop 0
	v_pk_add_f32 v[166:167], v[176:177], v[166:167]
	v_pk_add_f32 v[168:169], v[176:177], v[168:169]
	v_pk_add_f32 v[170:171], v[176:177], v[170:171]
	v_pk_add_f32 v[172:173], v[176:177], v[172:173]
	v_rcp_f32_e32 v166, v166
	v_rcp_f32_e32 v167, v167
	v_rcp_f32_e32 v168, v168
	v_rcp_f32_e32 v169, v169
	v_rcp_f32_e32 v170, v170
	v_rcp_f32_e32 v171, v171
	v_rcp_f32_e32 v172, v172
	v_rcp_f32_e32 v173, v173
	s_nop 0
	v_pk_mul_f32 v[166:167], v[62:63], v[166:167]
	v_pk_mul_f32 v[168:169], v[64:65], v[168:169]
	v_pk_mul_f32 v[170:171], v[54:55], v[170:171]
	v_pk_mul_f32 v[172:173], v[56:57], v[172:173]
	v_pk_mul_f32 v[58:59], v[58:59], v[166:167]
	v_pk_mul_f32 v[60:61], v[60:61], v[168:169]
	v_pk_mul_f32 v[50:51], v[50:51], v[170:171]
	v_pk_mul_f32 v[52:53], v[52:53], v[172:173]
	s_nop 0
	v_cvt_pk_bf16_f32 v62, v58, v59
	v_cvt_pk_bf16_f32 v63, v60, v61
	v_cvt_pk_bf16_f32 v64, v50, v51
	v_cvt_pk_bf16_f32 v65, v52, v53
	s_nop 1
	v_permlane16_swap_b32_e32 v62, v64
	v_permlane16_swap_b32_e32 v63, v65
	global_store_dwordx4 v[178:179], v[62:65], off
	v_mov_b32_e32 v181, 0
	v_lshl_add_u64 v[178:179], v[178:179], 0, v[180:181]
	v_pk_mul_f32 v[166:167], v[46:47], v[174:175]
	v_pk_mul_f32 v[168:169], v[48:49], v[174:175]
	v_pk_mul_f32 v[170:171], v[38:39], v[174:175]
	v_pk_mul_f32 v[172:173], v[40:41], v[174:175]
	v_exp_f32_e32 v166, v166
	v_exp_f32_e32 v167, v167
	v_exp_f32_e32 v168, v168
	v_exp_f32_e32 v169, v169
	v_exp_f32_e32 v170, v170
	v_exp_f32_e32 v171, v171
	v_exp_f32_e32 v172, v172
	v_exp_f32_e32 v173, v173
	s_nop 0
	v_pk_add_f32 v[166:167], v[176:177], v[166:167]
	v_pk_add_f32 v[168:169], v[176:177], v[168:169]
	v_pk_add_f32 v[170:171], v[176:177], v[170:171]
	v_pk_add_f32 v[172:173], v[176:177], v[172:173]
	v_rcp_f32_e32 v166, v166
	v_rcp_f32_e32 v167, v167
	v_rcp_f32_e32 v168, v168
	v_rcp_f32_e32 v169, v169
	v_rcp_f32_e32 v170, v170
	v_rcp_f32_e32 v171, v171
	v_rcp_f32_e32 v172, v172
	v_rcp_f32_e32 v173, v173
	s_nop 0
	v_pk_mul_f32 v[166:167], v[46:47], v[166:167]
	v_pk_mul_f32 v[168:169], v[48:49], v[168:169]
	v_pk_mul_f32 v[170:171], v[38:39], v[170:171]
	v_pk_mul_f32 v[172:173], v[40:41], v[172:173]
	v_pk_mul_f32 v[42:43], v[42:43], v[166:167]
	v_pk_mul_f32 v[44:45], v[44:45], v[168:169]
	v_pk_mul_f32 v[34:35], v[34:35], v[170:171]
	v_pk_mul_f32 v[36:37], v[36:37], v[172:173]
	s_nop 0
	v_cvt_pk_bf16_f32 v46, v42, v43
	v_cvt_pk_bf16_f32 v47, v44, v45
	v_cvt_pk_bf16_f32 v48, v34, v35
	v_cvt_pk_bf16_f32 v49, v36, v37
	s_nop 1
	v_permlane16_swap_b32_e32 v46, v48
	v_permlane16_swap_b32_e32 v47, v49
	global_store_dwordx4 v[178:179], v[46:49], off
	s_nop 1
	s_add_i32 s46, s46, s28
	v_mov_b32_e32 v37, 0
	s_cmp_ge_i32 s46, s33
	s_cbranch_scc1 .LBB0_1146
	s_mov_b32 s12, s10
	s_cmpk_gt_i32 s46, 0x9f
	s_mov_b64 s[2:3], -1
	s_cbranch_scc0 .LBB0_1184
	s_lshl_b32 s2, s46, 2
	s_add_i32 s2, s2, 0x7ffffd80
	s_and_b32 s13, s2, 0x7ffffff8
	s_and_b32 s2, s46, 1
	s_or_b32 s34, s2, 20
	s_mov_b64 s[2:3], 0

.LBB0_1233:
	s_add_i32 s44, s44, 2
	s_cmp_lg_u32 s44, 16
	s_waitcnt lgkmcnt(0)
	s_mov_b32 s98, 1
	s_cbranch_scc1 .LBB0_1202
	s_mov_b32 s98, 0
	v_mfma_f32_16x16x32_bf16 v[54:57], v[138:141], v[114:117], v[54:57]
	v_mfma_f32_16x16x32_bf16 v[46:49], v[142:145], v[114:117], v[46:49]
	v_mfma_f32_16x16x32_bf16 v[50:53], v[146:149], v[114:117], v[50:53]
	v_mfma_f32_16x16x32_bf16 v[42:45], v[150:153], v[114:117], v[42:45]
	v_mfma_f32_16x16x32_bf16 v[34:37], v[138:141], v[118:121], v[34:37]
	v_mfma_f32_16x16x32_bf16 v[30:33], v[142:145], v[118:121], v[30:33]
	v_mfma_f32_16x16x32_bf16 v[38:41], v[146:149], v[118:121], v[38:41]
	v_mfma_f32_16x16x32_bf16 v[26:29], v[150:153], v[118:121], v[26:29]
	s_nop 7
	s_nop 7
	v_mov_b32_e32 v144, v0
	v_and_b32_e32 v145, 15, v144
	v_ashrrev_i32_e32 v147, 2, v144
	v_lshl_or_b32 v145, s30, 8, v145
	v_and_b32_e32 v146, 0xc0, v144
	v_and_b32_e32 v147, 0xffffffc0, v147
	v_or_b32_e32 v145, s27, v145
	v_add_u32_e32 v150, v145, v147
	v_lshl_or_b32 v145, s28, 8, v146
	v_ashrrev_i32_e32 v145, 1, v145
	v_lshrrev_b32_e32 v144, 2, v144
	v_and_or_b32 v146, v144, 12, v145
	v_mov_b64_e32 v[144:145], s[6:7]
	v_ashrrev_i32_e32 v147, 31, v146
	v_lshlrev_b64 v[114:115], 1, v[146:147]
	v_mov_b32_e32 v106, 0xbfb8aa3b
	v_mov_b32_e32 v107, 0xbfb8aa3b
	v_mov_b32_e32 v108, 1.0
	v_mov_b32_e32 v109, 1.0
	v_mad_i64_i32 v[110:111], s[2:3], v150, s40, v[144:145]
	v_lshl_add_u64 v[110:111], v[110:111], 0, v[114:115]
	v_bfe_u32 v112, v0, 4, 1
	v_mul_u32_u24_e32 v112, 24, v112
	v_mov_b32_e32 v113, 0
	v_lshl_add_u64 v[110:111], v[110:111], 0, v[112:113]
	v_lshlrev_b32_e64 v112, 4, s40
	v_pk_mul_f32 v[98:99], v[58:59], v[106:107]
	v_pk_mul_f32 v[100:101], v[60:61], v[106:107]
	v_pk_mul_f32 v[102:103], v[82:83], v[106:107]
	v_pk_mul_f32 v[104:105], v[84:85], v[106:107]
	v_exp_f32_e32 v98, v98
	v_exp_f32_e32 v99, v99
	v_exp_f32_e32 v100, v100
	v_exp_f32_e32 v101, v101
	v_exp_f32_e32 v102, v102
	v_exp_f32_e32 v103, v103
	v_exp_f32_e32 v104, v104
	v_exp_f32_e32 v105, v105
	s_nop 0
	v_pk_add_f32 v[98:99], v[108:109], v[98:99]
	v_pk_add_f32 v[100:101], v[108:109], v[100:101]
	v_pk_add_f32 v[102:103], v[108:109], v[102:103]
	v_pk_add_f32 v[104:105], v[108:109], v[104:105]
	v_rcp_f32_e32 v98, v98
	v_rcp_f32_e32 v99, v99
	v_rcp_f32_e32 v100, v100
	v_rcp_f32_e32 v101, v101
	v_rcp_f32_e32 v102, v102
	v_rcp_f32_e32 v103, v103
	v_rcp_f32_e32 v104, v104
	v_rcp_f32_e32 v105, v105
	s_nop 0
	v_pk_mul_f32 v[98:99], v[58:59], v[98:99]
	v_pk_mul_f32 v[100:101], v[60:61], v[100:101]
	v_pk_mul_f32 v[102:103], v[82:83], v[102:103]
	v_pk_mul_f32 v[104:105], v[84:85], v[104:105]
	v_pk_mul_f32 v[86:87], v[86:87], v[98:99]
	v_pk_mul_f32 v[88:89], v[88:89], v[100:101]
	v_pk_mul_f32 v[78:79], v[78:79], v[102:103]
	v_pk_mul_f32 v[80:81], v[80:81], v[104:105]
	s_nop 0
	v_cvt_pk_bf16_f32 v58, v86, v87
	v_cvt_pk_bf16_f32 v59, v88, v89
	v_cvt_pk_bf16_f32 v60, v78, v79
	v_cvt_pk_bf16_f32 v61, v80, v81
	s_nop 1
	v_permlane16_swap_b32_e32 v58, v60
	v_permlane16_swap_b32_e32 v59, v61
	global_store_dwordx4 v[110:111], v[58:61], off
	v_mov_b32_e32 v113, 0
	v_lshl_add_u64 v[110:111], v[110:111], 0, v[112:113]
	v_pk_mul_f32 v[98:99], v[74:75], v[106:107]
	v_pk_mul_f32 v[100:101], v[76:77], v[106:107]
	v_pk_mul_f32 v[102:103], v[66:67], v[106:107]
	v_pk_mul_f32 v[104:105], v[68:69], v[106:107]
	v_exp_f32_e32 v98, v98
	v_exp_f32_e32 v99, v99
	v_exp_f32_e32 v100, v100
	v_exp_f32_e32 v101, v101
	v_exp_f32_e32 v102, v102
	v_exp_f32_e32 v103, v103
	v_exp_f32_e32 v104, v104
	v_exp_f32_e32 v105, v105
	s_nop 0
	v_pk_add_f32 v[98:99], v[108:109], v[98:99]
	v_pk_add_f32 v[100:101], v[108:109], v[100:101]
	v_pk_add_f32 v[102:103], v[108:109], v[102:103]
	v_pk_add_f32 v[104:105], v[108:109], v[104:105]
	v_rcp_f32_e32 v98, v98
	v_rcp_f32_e32 v99, v99
	v_rcp_f32_e32 v100, v100
	v_rcp_f32_e32 v101, v101
	v_rcp_f32_e32 v102, v102
	v_rcp_f32_e32 v103, v103
	v_rcp_f32_e32 v104, v104
	v_rcp_f32_e32 v105, v105
	s_nop 0
	v_pk_mul_f32 v[98:99], v[74:75], v[98:99]
	v_pk_mul_f32 v[100:101], v[76:77], v[100:101]
	v_pk_mul_f32 v[102:103], v[66:67], v[102:103]
	v_pk_mul_f32 v[104:105], v[68:69], v[104:105]
	v_pk_mul_f32 v[70:71], v[70:71], v[98:99]
	v_pk_mul_f32 v[72:73], v[72:73], v[100:101]
	v_pk_mul_f32 v[62:63], v[62:63], v[102:103]
	v_pk_mul_f32 v[64:65], v[64:65], v[104:105]
	s_nop 0
	v_cvt_pk_bf16_f32 v74, v70, v71
	v_cvt_pk_bf16_f32 v75, v72, v73
	v_cvt_pk_bf16_f32 v76, v62, v63
	v_cvt_pk_bf16_f32 v77, v64, v65
	s_nop 1
	v_permlane16_swap_b32_e32 v74, v76
	v_permlane16_swap_b32_e32 v75, v77
	global_store_dwordx4 v[110:111], v[74:77], off
	v_mov_b32_e32 v113, 0
	v_lshl_add_u64 v[110:111], v[110:111], 0, v[112:113]
	v_pk_mul_f32 v[98:99], v[54:55], v[106:107]
	v_pk_mul_f32 v[100:101], v[56:57], v[106:107]
	v_pk_mul_f32 v[102:103], v[46:47], v[106:107]
	v_pk_mul_f32 v[104:105], v[48:49], v[106:107]
	v_exp_f32_e32 v98, v98
	v_exp_f32_e32 v99, v99
	v_exp_f32_e32 v100, v100
	v_exp_f32_e32 v101, v101
	v_exp_f32_e32 v102, v102
	v_exp_f32_e32 v103, v103
	v_exp_f32_e32 v104, v104
	v_exp_f32_e32 v105, v105
	s_nop 0
	v_pk_add_f32 v[98:99], v[108:109], v[98:99]
	v_pk_add_f32 v[100:101], v[108:109], v[100:101]
	v_pk_add_f32 v[102:103], v[108:109], v[102:103]
	v_pk_add_f32 v[104:105], v[108:109], v[104:105]
	v_rcp_f32_e32 v98, v98
	v_rcp_f32_e32 v99, v99
	v_rcp_f32_e32 v100, v100
	v_rcp_f32_e32 v101, v101
	v_rcp_f32_e32 v102, v102
	v_rcp_f32_e32 v103, v103
	v_rcp_f32_e32 v104, v104
	v_rcp_f32_e32 v105, v105
	s_nop 0
	v_pk_mul_f32 v[98:99], v[54:55], v[98:99]
	v_pk_mul_f32 v[100:101], v[56:57], v[100:101]
	v_pk_mul_f32 v[102:103], v[46:47], v[102:103]
	v_pk_mul_f32 v[104:105], v[48:49], v[104:105]
	v_pk_mul_f32 v[50:51], v[50:51], v[98:99]
	v_pk_mul_f32 v[52:53], v[52:53], v[100:101]
	v_pk_mul_f32 v[42:43], v[42:43], v[102:103]
	v_pk_mul_f32 v[44:45], v[44:45], v[104:105]
	s_nop 0
	v_cvt_pk_bf16_f32 v54, v50, v51
	v_cvt_pk_bf16_f32 v55, v52, v53
	v_cvt_pk_bf16_f32 v56, v42, v43
	v_cvt_pk_bf16_f32 v57, v44, v45
	s_nop 1
	v_permlane16_swap_b32_e32 v54, v56
	v_permlane16_swap_b32_e32 v55, v57
	global_store_dwordx4 v[110:111], v[54:57], off
	v_mov_b32_e32 v113, 0
	v_lshl_add_u64 v[110:111], v[110:111], 0, v[112:113]
	v_pk_mul_f32 v[98:99], v[34:35], v[106:107]
	v_pk_mul_f32 v[100:101], v[36:37], v[106:107]
	v_pk_mul_f32 v[102:103], v[30:31], v[106:107]
	v_pk_mul_f32 v[104:105], v[32:33], v[106:107]
	v_exp_f32_e32 v98, v98
	v_exp_f32_e32 v99, v99
	v_exp_f32_e32 v100, v100
	v_exp_f32_e32 v101, v101
	v_exp_f32_e32 v102, v102
	v_exp_f32_e32 v103, v103
	v_exp_f32_e32 v104, v104
	v_exp_f32_e32 v105, v105
	s_nop 0
	v_pk_add_f32 v[98:99], v[108:109], v[98:99]
	v_pk_add_f32 v[100:101], v[108:109], v[100:101]
	v_pk_add_f32 v[102:103], v[108:109], v[102:103]
	v_pk_add_f32 v[104:105], v[108:109], v[104:105]
	v_rcp_f32_e32 v98, v98
	v_rcp_f32_e32 v99, v99
	v_rcp_f32_e32 v100, v100
	v_rcp_f32_e32 v101, v101
	v_rcp_f32_e32 v102, v102
	v_rcp_f32_e32 v103, v103
	v_rcp_f32_e32 v104, v104
	v_rcp_f32_e32 v105, v105
	s_nop 0
	v_pk_mul_f32 v[98:99], v[34:35], v[98:99]
	v_pk_mul_f32 v[100:101], v[36:37], v[100:101]
	v_pk_mul_f32 v[102:103], v[30:31], v[102:103]
	v_pk_mul_f32 v[104:105], v[32:33], v[104:105]
	v_pk_mul_f32 v[38:39], v[38:39], v[98:99]
	v_pk_mul_f32 v[40:41], v[40:41], v[100:101]
	v_pk_mul_f32 v[26:27], v[26:27], v[102:103]
	v_pk_mul_f32 v[28:29], v[28:29], v[104:105]
	s_nop 0
	v_cvt_pk_bf16_f32 v34, v38, v39
	v_cvt_pk_bf16_f32 v35, v40, v41
	v_cvt_pk_bf16_f32 v36, v26, v27
	v_cvt_pk_bf16_f32 v37, v28, v29
	s_nop 1
	v_permlane16_swap_b32_e32 v34, v36
	v_permlane16_swap_b32_e32 v35, v37
	global_store_dwordx4 v[110:111], v[34:37], off
	s_nop 1
	s_add_i32 s41, s41, s23
	v_mov_b32_e32 v29, 0
	s_cmp_ge_i32 s41, s29
	s_cbranch_scc1 .LBB0_1201
	s_mov_b32 s12, s10
	s_cmpk_gt_i32 s41, 0xaf
	s_cbranch_scc1 .LBB0_1201
	s_cmpk_gt_i32 s41, 0x9f
	s_mov_b64 s[2:3], -1
	s_cbranch_scc0 .LBB0_1238
	s_lshl_b32 s2, s41, 2
	s_add_i32 s2, s2, 0x7ffffd80
	s_and_b32 s13, s2, 0x7ffffff8
	s_and_b32 s2, s41, 1
	s_or_b32 s28, s2, 20
	s_mov_b64 s[2:3], 0
